# team barrier fast path: WAR-guard read and neighbour-team poll issued together with the team poll (one round trip instead of up to three)
# baseline (speedup 1.0000x reference)
; __device__ __forceinline__ unsigned xb_ld(unsigned* p)              { return __hip_atomic_load(p, __ATOMIC_RELAXED, __HIP_MEMORY_SCOPE_AGENT); }
; __device__ __forceinline__ unsigned xb_add(unsigned* p, unsigned v) { return __hip_atomic_fetch_add(p, v, __ATOMIC_RELAXED, __HIP_MEMORY_SCOPE_AGENT); }
; #define XB_SPIN(cond, bar) do { unsigned _sp = 0; while (cond) { __builtin_amdgcn_s_sleep(1); \
;     if ((++_sp & 255u) == 0u) { if (xb_ld(&(bar)[XB_TMO])) break; if (_sp > XB_SPIN_CAP) { atomicAdd(&(bar)[XB_TMO], 1u); break; } } } } while (0)
; __device__ __forceinline__ void xcd_barrier(const XcdBarrier& b) {
;     ...
;         const unsigned old = xb_add(&bar[XB_XSUB(b.x)], 1u);
;         const unsigned gen = old / nloc;
;         if (old + 1u == (gen + 1u) * nloc) {
;             __builtin_amdgcn_fence(__ATOMIC_RELEASE, "agent");
;             asm volatile("s_waitcnt vmcnt(0)" ::: "memory");
;             const unsigned og = xb_add(&bar[XB_TOP], 1u);
;             const unsigned tg = og / nx;
;             if (og + 1u == (tg + 1u) * nx) xb_add(&bar[XB_TOPGEN], 1u);
;             else XB_SPIN(xb_ld(&bar[XB_TOPGEN]) == tg, bar);
;             __builtin_amdgcn_fence(__ATOMIC_ACQUIRE, "agent");
;             xb_add(&bar[XB_XGEN(b.x)], 1u);
;             asm volatile("s_waitcnt vmcnt(0)" ::: "memory");
;         } else {
;             XB_SPIN(xb_ld(&bar[XB_XGEN(b.x)]) == gen, bar);
;             __builtin_amdgcn_fence(__ATOMIC_ACQUIRE, "agent");
;             asm volatile("s_waitcnt vmcnt(0)" ::: "memory");
.Ltb482_fast:
	s_mov_b64 exec, -1
	v_lshlrev_b32_e32 v4, 5, v195
	global_load_dword v5, v4, s[8:9] sc1
	s_mov_b64 exec, 1
	global_atomic_add v0, v1, s[8:9]
	buffer_inv sc1

; __device__ __forceinline__ unsigned xb_ld(unsigned* p)              { return __hip_atomic_load(p, __ATOMIC_RELAXED, __HIP_MEMORY_SCOPE_AGENT); }
; __device__ __forceinline__ unsigned xb_add(unsigned* p, unsigned v) { return __hip_atomic_fetch_add(p, v, __ATOMIC_RELAXED, __HIP_MEMORY_SCOPE_AGENT); }
; #define XB_SPIN(cond, bar) do { unsigned _sp = 0; while (cond) { __builtin_amdgcn_s_sleep(1); \
;     if ((++_sp & 255u) == 0u) { if (xb_ld(&(bar)[XB_TMO])) break; if (_sp > XB_SPIN_CAP) { atomicAdd(&(bar)[XB_TMO], 1u); break; } } } } while (0)
; __device__ __forceinline__ void xcd_barrier(const XcdBarrier& b) {
;     ...
;         const unsigned old = xb_add(&bar[XB_XSUB(b.x)], 1u);
;         const unsigned gen = old / nloc;
;         if (old + 1u == (gen + 1u) * nloc) {
;             __builtin_amdgcn_fence(__ATOMIC_RELEASE, "agent");
;             asm volatile("s_waitcnt vmcnt(0)" ::: "memory");
;             const unsigned og = xb_add(&bar[XB_TOP], 1u);
;             const unsigned tg = og / nx;
;             if (og + 1u == (tg + 1u) * nx) xb_add(&bar[XB_TOPGEN], 1u);
;             else XB_SPIN(xb_ld(&bar[XB_TOPGEN]) == tg, bar);
;             __builtin_amdgcn_fence(__ATOMIC_ACQUIRE, "agent");
;             xb_add(&bar[XB_XGEN(b.x)], 1u);
;             asm volatile("s_waitcnt vmcnt(0)" ::: "memory");
;         } else {
;             XB_SPIN(xb_ld(&bar[XB_XGEN(b.x)]) == gen, bar);
;             __builtin_amdgcn_fence(__ATOMIC_ACQUIRE, "agent");
;             asm volatile("s_waitcnt vmcnt(0)" ::: "memory");
.Ltb482_frel:
	s_mov_b64 exec, -1
	v_cmp_gt_u32_e32 vcc, 8, v5
	s_cmp_lg_u64 vcc, 0
	s_cbranch_scc0 .Ltb482_fgd
	s_mov_b64 exec, -1
	v_lshlrev_b32_e32 v4, 5, v195

; __device__ __forceinline__ unsigned xb_ld(unsigned* p)              { return __hip_atomic_load(p, __ATOMIC_RELAXED, __HIP_MEMORY_SCOPE_AGENT); }
; __device__ __forceinline__ unsigned xb_add(unsigned* p, unsigned v) { return __hip_atomic_fetch_add(p, v, __ATOMIC_RELAXED, __HIP_MEMORY_SCOPE_AGENT); }
; #define XB_SPIN(cond, bar) do { unsigned _sp = 0; while (cond) { __builtin_amdgcn_s_sleep(1); \
;     if ((++_sp & 255u) == 0u) { if (xb_ld(&(bar)[XB_TMO])) break; if (_sp > XB_SPIN_CAP) { atomicAdd(&(bar)[XB_TMO], 1u); break; } } } } while (0)
; __device__ __forceinline__ void xcd_barrier(const XcdBarrier& b) {
;     ...
;         const unsigned old = xb_add(&bar[XB_XSUB(b.x)], 1u);
;         const unsigned gen = old / nloc;
;         if (old + 1u == (gen + 1u) * nloc) {
;             __builtin_amdgcn_fence(__ATOMIC_RELEASE, "agent");
;             asm volatile("s_waitcnt vmcnt(0)" ::: "memory");
;             const unsigned og = xb_add(&bar[XB_TOP], 1u);
;             const unsigned tg = og / nx;
;             if (og + 1u == (tg + 1u) * nx) xb_add(&bar[XB_TOPGEN], 1u);
;             else XB_SPIN(xb_ld(&bar[XB_TOPGEN]) == tg, bar);
;             __builtin_amdgcn_fence(__ATOMIC_ACQUIRE, "agent");
;             xb_add(&bar[XB_XGEN(b.x)], 1u);
;             asm volatile("s_waitcnt vmcnt(0)" ::: "memory");
;         } else {
;             XB_SPIN(xb_ld(&bar[XB_XGEN(b.x)]) == gen, bar);
;             __builtin_amdgcn_fence(__ATOMIC_ACQUIRE, "agent");
;             asm volatile("s_waitcnt vmcnt(0)" ::: "memory");
.Ltb675_fast:
	v_mov_b32_e32 v7, v0
	s_bitcmp1_b32 s2, 6
	s_cbranch_scc1 .Ltb675_fnn
	s_cmp_lt_u32 s2, 8
	s_cbranch_scc1 .Ltb675_fnn
	s_bfe_u32 s13, s2, 0x30003
	s_add_u32 s13, s13, 7
	s_and_b32 s13, s13, 7
	s_and_b32 s3, s2, 7
	s_lshl_b32 s3, s3, 3
	s_or_b32 s3, s3, s13
	s_lshl_b32 s3, s3, 5
	v_mov_b32_e32 v7, s3

; __device__ __forceinline__ unsigned xb_ld(unsigned* p)              { return __hip_atomic_load(p, __ATOMIC_RELAXED, __HIP_MEMORY_SCOPE_AGENT); }
; __device__ __forceinline__ unsigned xb_add(unsigned* p, unsigned v) { return __hip_atomic_fetch_add(p, v, __ATOMIC_RELAXED, __HIP_MEMORY_SCOPE_AGENT); }
; #define XB_SPIN(cond, bar) do { unsigned _sp = 0; while (cond) { __builtin_amdgcn_s_sleep(1); \
;     if ((++_sp & 255u) == 0u) { if (xb_ld(&(bar)[XB_TMO])) break; if (_sp > XB_SPIN_CAP) { atomicAdd(&(bar)[XB_TMO], 1u); break; } } } } while (0)
; __device__ __forceinline__ void xcd_barrier(const XcdBarrier& b) {
;     ...
;         const unsigned old = xb_add(&bar[XB_XSUB(b.x)], 1u);
;         const unsigned gen = old / nloc;
;         if (old + 1u == (gen + 1u) * nloc) {
;             __builtin_amdgcn_fence(__ATOMIC_RELEASE, "agent");
;             asm volatile("s_waitcnt vmcnt(0)" ::: "memory");
;             const unsigned og = xb_add(&bar[XB_TOP], 1u);
;             const unsigned tg = og / nx;
;             if (og + 1u == (tg + 1u) * nx) xb_add(&bar[XB_TOPGEN], 1u);
;             else XB_SPIN(xb_ld(&bar[XB_TOPGEN]) == tg, bar);
;             __builtin_amdgcn_fence(__ATOMIC_ACQUIRE, "agent");
;             xb_add(&bar[XB_XGEN(b.x)], 1u);
;             asm volatile("s_waitcnt vmcnt(0)" ::: "memory");
;         } else {
;             XB_SPIN(xb_ld(&bar[XB_XGEN(b.x)]) == gen, bar);
;             __builtin_amdgcn_fence(__ATOMIC_ACQUIRE, "agent");
;             asm volatile("s_waitcnt vmcnt(0)" ::: "memory");
.Ltb675_spin:
	global_load_dword v3, v0, s[8:9] sc1
	global_load_dword v8, v7, s[8:9] sc1
	s_waitcnt vmcnt(0)
	v_cmp_ge_u32_e32 vcc, v3, v2
	v_cmp_ge_u32_e64 s[52:53], v8, v2
	s_and_b64 vcc, vcc, s[52:53]
	s_cbranch_vccnz .Ltb675_frel
	s_sleep 1
	s_add_u32 s15, s15, 1
	s_cmp_lt_u32 s15, 0x400000
	s_cbranch_scc1 .Ltb675_spin

; __device__ __forceinline__ unsigned xb_ld(unsigned* p)              { return __hip_atomic_load(p, __ATOMIC_RELAXED, __HIP_MEMORY_SCOPE_AGENT); }
; __device__ __forceinline__ unsigned xb_add(unsigned* p, unsigned v) { return __hip_atomic_fetch_add(p, v, __ATOMIC_RELAXED, __HIP_MEMORY_SCOPE_AGENT); }
; #define XB_SPIN(cond, bar) do { unsigned _sp = 0; while (cond) { __builtin_amdgcn_s_sleep(1); \
;     if ((++_sp & 255u) == 0u) { if (xb_ld(&(bar)[XB_TMO])) break; if (_sp > XB_SPIN_CAP) { atomicAdd(&(bar)[XB_TMO], 1u); break; } } } } while (0)
; __device__ __forceinline__ void xcd_barrier(const XcdBarrier& b) {
;     ...
;         const unsigned old = xb_add(&bar[XB_XSUB(b.x)], 1u);
;         const unsigned gen = old / nloc;
;         if (old + 1u == (gen + 1u) * nloc) {
;             __builtin_amdgcn_fence(__ATOMIC_RELEASE, "agent");
;             asm volatile("s_waitcnt vmcnt(0)" ::: "memory");
;             const unsigned og = xb_add(&bar[XB_TOP], 1u);
;             const unsigned tg = og / nx;
;             if (og + 1u == (tg + 1u) * nx) xb_add(&bar[XB_TOPGEN], 1u);
;             else XB_SPIN(xb_ld(&bar[XB_TOPGEN]) == tg, bar);
;             __builtin_amdgcn_fence(__ATOMIC_ACQUIRE, "agent");
;             xb_add(&bar[XB_XGEN(b.x)], 1u);
;             asm volatile("s_waitcnt vmcnt(0)" ::: "memory");
;         } else {
;             XB_SPIN(xb_ld(&bar[XB_XGEN(b.x)]) == gen, bar);
;             __builtin_amdgcn_fence(__ATOMIC_ACQUIRE, "agent");
;             asm volatile("s_waitcnt vmcnt(0)" ::: "memory");
.Ltb1039_frel:
	s_mov_b64 exec, -1
	v_cmp_gt_u32_e32 vcc, 28, v5
	s_cmp_lg_u64 vcc, 0
	s_cbranch_scc0 .Ltb1039_fgd
	s_mov_b64 exec, -1
	v_lshlrev_b32_e32 v4, 5, v195

; __device__ __forceinline__ unsigned xb_ld(unsigned* p)              { return __hip_atomic_load(p, __ATOMIC_RELAXED, __HIP_MEMORY_SCOPE_AGENT); }
; __device__ __forceinline__ unsigned xb_add(unsigned* p, unsigned v) { return __hip_atomic_fetch_add(p, v, __ATOMIC_RELAXED, __HIP_MEMORY_SCOPE_AGENT); }
; #define XB_SPIN(cond, bar) do { unsigned _sp = 0; while (cond) { __builtin_amdgcn_s_sleep(1); \
;     if ((++_sp & 255u) == 0u) { if (xb_ld(&(bar)[XB_TMO])) break; if (_sp > XB_SPIN_CAP) { atomicAdd(&(bar)[XB_TMO], 1u); break; } } } } while (0)
; __device__ __forceinline__ void xcd_barrier(const XcdBarrier& b) {
;     ...
;         const unsigned old = xb_add(&bar[XB_XSUB(b.x)], 1u);
;         const unsigned gen = old / nloc;
;         if (old + 1u == (gen + 1u) * nloc) {
;             __builtin_amdgcn_fence(__ATOMIC_RELEASE, "agent");
;             asm volatile("s_waitcnt vmcnt(0)" ::: "memory");
;             const unsigned og = xb_add(&bar[XB_TOP], 1u);
;             const unsigned tg = og / nx;
;             if (og + 1u == (tg + 1u) * nx) xb_add(&bar[XB_TOPGEN], 1u);
;             else XB_SPIN(xb_ld(&bar[XB_TOPGEN]) == tg, bar);
;             __builtin_amdgcn_fence(__ATOMIC_ACQUIRE, "agent");
;             xb_add(&bar[XB_XGEN(b.x)], 1u);
;             asm volatile("s_waitcnt vmcnt(0)" ::: "memory");
;         } else {
;             XB_SPIN(xb_ld(&bar[XB_XGEN(b.x)]) == gen, bar);
;             __builtin_amdgcn_fence(__ATOMIC_ACQUIRE, "agent");
;             asm volatile("s_waitcnt vmcnt(0)" ::: "memory");
.Ltb1309_frel:
	s_mov_b64 exec, -1
	v_cmp_gt_u32_e32 vcc, 40, v5
	s_cmp_lg_u64 vcc, 0
	s_cbranch_scc0 .Ltb1309_fgd
	s_mov_b64 exec, -1
	v_lshlrev_b32_e32 v4, 5, v195
